# phase-4 epilogue: 16 serial gate loads (vmcnt(0) each) -> rolling prefetch, 6 in flight into dead K-loop fragment registers, counted waits
# speedup vs baseline: 1.0048x; 1.0048x over previous
; #define GL_LOAD(s_, kt_) if (VAR != 1) { a##s_##0 = GL_A(0, kt_); a##s_##1 = GL_A(1, kt_); a##s_##2 = GL_A(2, kt_); a##s_##3 = GL_A(3, kt_); b##s_##0 = GL_B(0, kt_); b##s_##1 = GL_B(1, kt_); b##s_##2 = GL_B(2, kt_); b##s_##3 = GL_B(3, kt_); }
; #define LDS_STORE(s_, buf_) if (VAR != 2) { LDS_ST1(sA, 0, buf_, a##s_##0) LDS_ST1(sA, 1, buf_, a##s_##1) LDS_ST1(sA, 2, buf_, a##s_##2) LDS_ST1(sA, 3, buf_, a##s_##3) LDS_ST1(sB, 0, buf_, b##s_##0) LDS_ST1(sB, 1, buf_, b##s_##1) LDS_ST1(sB, 2, buf_, b##s_##2) LDS_ST1(sB, 3, buf_, b##s_##3) }
;     ...
;   GL_LOAD(0, 0)
;   GL_LOAD(1, 1)
;   LDS_STORE(0, 0)
;   if (VAR != 4) __syncthreads();
; #pragma unroll
;   for (int kt = 0; kt < nk; kt += 2) {
;     if (kt + 2 < nk) { GL_LOAD(0, kt + 2) }
;     MMA_TILE(0)
;     LDS_STORE(1, 1)
;     if (VAR != 4) __syncthreads();
;     if (kt + 3 < nk) { GL_LOAD(1, kt + 3) }
;     MMA_TILE(1)
; DI void phase_merge(const Params& P, int l, char* smem) {
;     ...
;     for (int br = 0; br < 3; ++br) {
;       f32x4 acc[4][4]; zero_acc(acc);
;       const int ycol = br == 0 ? C_AQ : (br == 1 ? C_BQ : C_CQ);
;       const bf16_t* Wb = W + (br == 0 ? WO_BRA : (br == 1 ? WO_BRB : WO_BRC));
;       gemm_kloop<false, true, 8>(acc, Pb + (size_t)m0 * PW + ycol, PW, Wb + (size_t)n0 * 512, 512, smem);
.LBB0_1161:
	s_cmp_lg_u32 s4, 0
	s_cselect_b64 s[6:7], -1, 0
	s_cmpk_eq_i32 s4, 0x800
	s_mov_b32 s8, 0x860000
	s_cselect_b32 s17, 0x400, s36
	s_cselect_b32 s20, s8, 0x8e0000
	s_cmp_eq_u32 s4, 0
	s_cselect_b64 s[8:9], -1, 0
	s_and_b64 s[18:19], s[8:9], exec
	s_cselect_b32 s17, 0, s17
	s_cselect_b32 s20, 0x7e0000, s20
	s_lshl_b32 s17, s17, 1
	s_add_u32 s18, s13, s17
	s_addc_u32 s19, s14, 0
	v_mov_b32_e32 v56, v148
	v_mov_b64_e32 v[6:7], s[18:19]
	v_ashrrev_i32_e32 v16, 3, v56
	v_lshlrev_b32_e32 v57, 4, v56
	v_mad_i64_i32 v[0:1], s[18:19], v16, s0, v[6:7]
	v_and_b32_e32 v150, 0x70, v57
	v_add_u32_e32 v18, 32, v16
	s_lshl_b32 s17, s20, 1
	v_lshl_add_u64 v[0:1], v[0:1], 0, v[150:151]
	v_mad_i64_i32 v[2:3], s[18:19], v18, s0, v[6:7]
	v_add_u32_e32 v52, 64, v16
	s_add_u32 s20, s15, s17
	v_ashrrev_i32_e32 v17, 31, v16
	global_load_dwordx4 v[20:23], v[0:1], off
	v_lshl_add_u64 v[2:3], v[2:3], 0, v[150:151]
	v_mad_i64_i32 v[4:5], s[18:19], v52, s0, v[6:7]
	v_add_u32_e32 v54, 0x60, v16
	s_addc_u32 s21, s16, 0
	v_ashrrev_i32_e32 v19, 31, v18
	global_load_dwordx4 v[24:27], v[2:3], off
	v_lshl_add_u64 v[4:5], v[4:5], 0, v[150:151]
	v_mad_i64_i32 v[6:7], s[18:19], v54, s0, v[6:7]
	v_lshlrev_b64 v[8:9], 10, v[16:17]
	v_ashrrev_i32_e32 v53, 31, v52
	global_load_dwordx4 v[28:31], v[4:5], off
	v_lshl_add_u64 v[6:7], v[6:7], 0, v[150:151]
	v_lshl_add_u64 v[8:9], s[20:21], 0, v[8:9]
	v_lshlrev_b64 v[10:11], 10, v[18:19]
	v_ashrrev_i32_e32 v55, 31, v54
	global_load_dwordx4 v[32:35], v[6:7], off
	v_lshl_add_u64 v[8:9], v[8:9], 0, v[150:151]
	v_lshl_add_u64 v[10:11], s[20:21], 0, v[10:11]
	v_lshlrev_b64 v[12:13], 10, v[52:53]
	global_load_dwordx4 v[36:39], v[8:9], off
	v_lshl_add_u64 v[10:11], v[10:11], 0, v[150:151]
	v_lshl_add_u64 v[12:13], s[20:21], 0, v[12:13]
	v_lshlrev_b64 v[14:15], 10, v[54:55]
	global_load_dwordx4 v[40:43], v[10:11], off
	v_lshl_add_u64 v[12:13], v[12:13], 0, v[150:151]
	v_lshl_add_u64 v[14:15], s[20:21], 0, v[14:15]
	global_load_dwordx4 v[44:47], v[12:13], off
	v_lshl_add_u64 v[14:15], v[14:15], 0, v[150:151]
	global_load_dwordx4 v[48:51], v[14:15], off
	v_lshlrev_b32_e32 v19, 3, v56
	v_and_b32_e32 v108, 48, v56
	v_and_b32_e32 v17, 15, v56
	v_lshrrev_b32_e32 v53, 1, v56
	v_lshlrev_b32_e32 v55, 7, v56
	v_and_b32_e32 v109, 0x70, v19
	v_bitop3_b32 v115, v19, v108, s23 bitop3:0x6c
	v_bitop3_b32 v19, v57, s23, v56 bitop3:0x48
	v_and_or_b32 v136, v53, s24, v17
	v_and_b32_e32 v150, 0x2780, v55
	v_lshl_or_b32 v16, v16, 7, v19
	v_lshl_or_b32 v17, v18, 7, v19
	v_lshl_or_b32 v18, v52, 7, v19
	v_lshl_or_b32 v19, v54, 7, v19
	global_load_dwordx4 v[52:55], v[0:1], off offset:128
	global_load_dwordx4 v[56:59], v[2:3], off offset:128
	global_load_dwordx4 v[104:107], v[4:5], off offset:128
	global_load_dwordx4 v[116:119], v[6:7], off offset:128
	global_load_dwordx4 v[120:123], v[8:9], off offset:128
	global_load_dwordx4 v[124:127], v[10:11], off offset:128
	global_load_dwordx4 v[128:131], v[12:13], off offset:128
	global_load_dwordx4 v[132:135], v[14:15], off offset:128
	s_and_b64 vcc, s[8:9], exec
	s_waitcnt vmcnt(15)
	ds_write_b128 v16, v[20:23]
	s_waitcnt vmcnt(14)
	ds_write_b128 v17, v[24:27]
	s_waitcnt vmcnt(13)
	ds_write_b128 v18, v[28:31]
	s_waitcnt vmcnt(12)
	ds_write_b128 v19, v[32:35]
	s_waitcnt vmcnt(11)
	ds_write_b128 v16, v[36:39] offset:32768
	s_waitcnt vmcnt(10)
	ds_write_b128 v17, v[40:43] offset:32768
	s_waitcnt vmcnt(9)
	ds_write_b128 v18, v[44:47] offset:32768
	s_waitcnt vmcnt(8)
	ds_write_b128 v19, v[48:51] offset:32768
	v_or_b32_e32 v20, v150, v115
	s_waitcnt lgkmcnt(0)
	s_barrier
	s_setprio 1
	ds_read_b128 v[22:25], v20 offset:32768
	v_lshlrev_b32_e32 v50, 7, v136
	v_bitop3_b32 v21, v50, v109, v108 bitop3:0xf6
	ds_read_b128 v[30:33], v21
	s_waitcnt lgkmcnt(0)
	v_mfma_f32_16x16x32_f16 v[38:41], v[22:25], v[30:33], 0
	ds_read_b128 v[26:29], v20 offset:34816
	ds_read_b128 v[34:37], v21 offset:2048
	s_waitcnt lgkmcnt(0)
	v_mfma_f32_16x16x32_f16 v[144:147], v[22:25], v[34:37], 0
	ds_read_b128 v[42:45], v20 offset:36864
	ds_read_b128 v[162:165], v21 offset:4096
	s_waitcnt lgkmcnt(0)
	v_mfma_f32_16x16x32_f16 v[190:193], v[22:25], v[162:165], 0
	ds_read_b128 v[136:139], v20 offset:38912
	ds_read_b128 v[166:169], v21 offset:6144
	s_waitcnt lgkmcnt(0)
	v_mfma_f32_16x16x32_f16 v[202:205], v[22:25], v[166:169], 0
	v_lshl_add_u64 v[108:109], v[80:81], 0, s[4:5]
	v_mfma_f32_16x16x32_f16 v[46:49], v[26:29], v[30:33], 0
	v_xor_b32_e32 v22, 64, v115
	v_mfma_f32_16x16x32_f16 v[140:143], v[42:45], v[30:33], 0
	v_or_b32_e32 v23, v150, v22
	v_mfma_f32_16x16x32_f16 v[30:33], v[136:139], v[30:33], 0
	ds_read_b128 v[206:209], v23 offset:32768
	v_mfma_f32_16x16x32_f16 v[154:157], v[26:29], v[34:37], 0
	ds_read_b128 v[224:227], v23 offset:36864
	v_mfma_f32_16x16x32_f16 v[158:161], v[42:45], v[34:37], 0
	ds_read_b128 v[228:231], v23 offset:38912
	v_mfma_f32_16x16x32_f16 v[34:37], v[136:139], v[34:37], 0
	v_bitop3_b32 v22, v50, v115, 64 bitop3:0xf6
	v_mfma_f32_16x16x32_f16 v[194:197], v[26:29], v[162:165], 0
	ds_read_b128 v[210:213], v22
	v_mfma_f32_16x16x32_f16 v[198:201], v[42:45], v[162:165], 0
	ds_read_b128 v[220:223], v22 offset:2048
	v_mfma_f32_16x16x32_f16 v[162:165], v[136:139], v[162:165], 0
	s_waitcnt vmcnt(7)
	ds_write_b128 v16, v[52:55] offset:16384
	v_mfma_f32_16x16x32_f16 v[24:27], v[26:29], v[166:169], 0
	s_waitcnt vmcnt(6)
	ds_write_b128 v17, v[56:59] offset:16384
	v_mfma_f32_16x16x32_f16 v[42:45], v[42:45], v[166:169], 0
	s_waitcnt vmcnt(5)
	ds_write_b128 v18, v[104:107] offset:16384
	v_mfma_f32_16x16x32_f16 v[136:139], v[136:139], v[166:169], 0
	ds_read_b128 v[166:169], v23 offset:34816
	s_waitcnt lgkmcnt(5)
; #define GL_LOAD(s_, kt_) if (VAR != 1) { a##s_##0 = GL_A(0, kt_); a##s_##1 = GL_A(1, kt_); a##s_##2 = GL_A(2, kt_); a##s_##3 = GL_A(3, kt_); b##s_##0 = GL_B(0, kt_); b##s_##1 = GL_B(1, kt_); b##s_##2 = GL_B(2, kt_); b##s_##3 = GL_B(3, kt_); }
; #define LDS_STORE(s_, buf_) if (VAR != 2) { LDS_ST1(sA, 0, buf_, a##s_##0) LDS_ST1(sA, 1, buf_, a##s_##1) LDS_ST1(sA, 2, buf_, a##s_##2) LDS_ST1(sA, 3, buf_, a##s_##3) LDS_ST1(sB, 0, buf_, b##s_##0) LDS_ST1(sB, 1, buf_, b##s_##1) LDS_ST1(sB, 2, buf_, b##s_##2) LDS_ST1(sB, 3, buf_, b##s_##3) }
;     ...
;   for (int kt = 0; kt < nk; kt += 2) {
;     if (kt + 2 < nk) { GL_LOAD(0, kt + 2) }
;     MMA_TILE(0)
;     LDS_STORE(1, 1)
;     if (VAR != 4) __syncthreads();
;     if (kt + 3 < nk) { GL_LOAD(1, kt + 3) }
;     MMA_TILE(1)
;     if (kt + 2 < nk) { LDS_STORE(0, 0) }
;     if (VAR != 4) __syncthreads();
	v_mfma_f32_16x16x32_f16 v[38:41], v[206:209], v[210:213], v[38:41]
	s_waitcnt vmcnt(4)
	ds_write_b128 v19, v[116:119] offset:16384
	v_mfma_f32_16x16x32_f16 v[140:143], v[224:227], v[210:213], v[140:143]
	s_waitcnt vmcnt(3)
	ds_write_b128 v16, v[120:123] offset:49152
	v_mfma_f32_16x16x32_f16 v[28:31], v[228:231], v[210:213], v[30:33]
	s_waitcnt vmcnt(2)
	ds_write_b128 v17, v[124:127] offset:49152
	s_waitcnt lgkmcnt(7)
	v_mfma_f32_16x16x32_f16 v[144:147], v[206:209], v[220:223], v[144:147]
	s_waitcnt vmcnt(1)
	ds_write_b128 v18, v[128:131] offset:49152
	v_mfma_f32_16x16x32_f16 v[158:161], v[224:227], v[220:223], v[158:161]
	s_waitcnt vmcnt(0)
	ds_write_b128 v19, v[132:135] offset:49152
	v_mfma_f32_16x16x32_f16 v[32:35], v[228:231], v[220:223], v[34:37]
	s_waitcnt lgkmcnt(5)
	v_mfma_f32_16x16x32_f16 v[46:49], v[166:169], v[210:213], v[46:49]
	ds_read_b128 v[210:213], v22 offset:4096
	v_mfma_f32_16x16x32_f16 v[154:157], v[166:169], v[220:223], v[154:157]
	ds_read_b128 v[220:223], v22 offset:6144
	s_waitcnt lgkmcnt(1)
	v_mfma_f32_16x16x32_f16 v[190:193], v[206:209], v[210:213], v[190:193]
	s_waitcnt lgkmcnt(0)
	v_mfma_f32_16x16x32_f16 v[202:205], v[206:209], v[220:223], v[202:205]
	global_load_dwordx4 v[206:209], v[0:1], off offset:256
	v_mfma_f32_16x16x32_f16 v[194:197], v[166:169], v[210:213], v[194:197]
	v_mfma_f32_16x16x32_f16 v[24:27], v[166:169], v[220:223], v[24:27]
	v_mfma_f32_16x16x32_f16 v[198:201], v[224:227], v[210:213], v[198:201]
	v_mfma_f32_16x16x32_f16 v[162:165], v[228:231], v[210:213], v[162:165]
	global_load_dwordx4 v[210:213], v[2:3], off offset:256
	global_load_dwordx4 v[232:235], v[4:5], off offset:256
	global_load_dwordx4 v[236:239], v[6:7], off offset:256
	global_load_dwordx4 v[166:169], v[8:9], off offset:256
	global_load_dwordx4 v[240:243], v[10:11], off offset:256
	global_load_dwordx4 v[244:247], v[12:13], off offset:256
	global_load_dwordx4 v[248:251], v[14:15], off offset:256
	s_waitcnt lgkmcnt(0)
	s_barrier
	v_mfma_f32_16x16x32_f16 v[54:57], v[228:231], v[220:223], v[136:139]
	ds_read_b128 v[50:53], v20 offset:49152
	v_mfma_f32_16x16x32_f16 v[42:45], v[224:227], v[220:223], v[42:45]
	ds_read_b128 v[104:107], v20 offset:51200
	ds_read_b128 v[116:119], v21 offset:16384
	s_waitcnt lgkmcnt(0)
	v_mfma_f32_16x16x32_f16 v[36:39], v[50:53], v[116:119], v[38:41]
	ds_read_b128 v[120:123], v21 offset:18432
	v_mfma_f32_16x16x32_f16 v[46:49], v[104:107], v[116:119], v[46:49]
	ds_read_b128 v[124:127], v20 offset:53248
	s_waitcnt lgkmcnt(0)
	v_mfma_f32_16x16x32_f16 v[132:135], v[124:127], v[116:119], v[140:143]
	ds_read_b128 v[128:131], v20 offset:55296
	s_waitcnt lgkmcnt(0)
	v_mfma_f32_16x16x32_f16 v[28:31], v[128:131], v[116:119], v[28:31]
	v_mfma_f32_16x16x32_f16 v[116:119], v[50:53], v[120:123], v[144:147]
	s_nop 2
	ds_read_b128 v[144:147], v21 offset:22528
	s_waitcnt vmcnt(7)
	ds_write_b128 v16, v[206:209]
	v_mfma_f32_16x16x32_f16 v[136:139], v[104:107], v[120:123], v[154:157]
	s_waitcnt vmcnt(6)
	ds_write_b128 v17, v[210:213]
	s_waitcnt vmcnt(5)
	ds_write_b128 v18, v[232:235]
	v_mfma_f32_16x16x32_f16 v[140:143], v[124:127], v[120:123], v[158:161]
	s_waitcnt vmcnt(4)
	ds_write_b128 v19, v[236:239]
	s_waitcnt vmcnt(3)
	ds_write_b128 v16, v[166:169] offset:32768
	v_mfma_f32_16x16x32_f16 v[32:35], v[128:131], v[120:123], v[32:35]
	ds_read_b128 v[120:123], v21 offset:20480
	s_waitcnt lgkmcnt(0)
	v_mfma_f32_16x16x32_f16 v[154:157], v[50:53], v[120:123], v[190:193]
	s_waitcnt vmcnt(2)
	ds_write_b128 v17, v[240:243] offset:32768
	v_mfma_f32_16x16x32_f16 v[50:53], v[50:53], v[144:147], v[202:205]
	s_waitcnt vmcnt(1)
	ds_write_b128 v18, v[244:247] offset:32768
	v_mfma_f32_16x16x32_f16 v[158:161], v[104:107], v[120:123], v[194:197]
	s_nop 2
	ds_read_b128 v[194:197], v23 offset:55296
	v_mfma_f32_16x16x32_f16 v[24:27], v[104:107], v[144:147], v[24:27]
	ds_read_b128 v[104:107], v23 offset:49152
	v_mfma_f32_16x16x32_f16 v[190:193], v[124:127], v[120:123], v[198:201]
	s_waitcnt vmcnt(0)
	ds_write_b128 v19, v[248:251] offset:32768
	v_mfma_f32_16x16x32_f16 v[40:43], v[124:127], v[144:147], v[42:45]
	ds_read_b128 v[124:127], v23 offset:51200
	v_mfma_f32_16x16x32_f16 v[120:123], v[128:131], v[120:123], v[162:165]
	s_nop 2
	ds_read_b128 v[162:165], v23 offset:53248
	v_mfma_f32_16x16x32_f16 v[54:57], v[128:131], v[144:147], v[54:57]
	ds_read_b128 v[128:131], v22 offset:16384
	s_waitcnt lgkmcnt(0)
	v_mfma_f32_16x16x32_f16 v[36:39], v[104:107], v[128:131], v[36:39]
	ds_read_b128 v[144:147], v22 offset:18432
	s_waitcnt lgkmcnt(0)
	v_mfma_f32_16x16x32_f16 v[116:119], v[104:107], v[144:147], v[116:119]
	v_mfma_f32_16x16x32_f16 v[44:47], v[124:127], v[128:131], v[46:49]
	v_mfma_f32_16x16x32_f16 v[132:135], v[162:165], v[128:131], v[132:135]
	v_mfma_f32_16x16x32_f16 v[28:31], v[194:197], v[128:131], v[28:31]
	v_mfma_f32_16x16x32_f16 v[128:131], v[124:127], v[144:147], v[136:139]
	v_mfma_f32_16x16x32_f16 v[136:139], v[162:165], v[144:147], v[140:143]
	s_nop 2
	ds_read_b128 v[140:143], v22 offset:20480
	v_mfma_f32_16x16x32_f16 v[32:35], v[194:197], v[144:147], v[32:35]
	ds_read_b128 v[144:147], v22 offset:22528
	s_waitcnt lgkmcnt(1)
	v_mfma_f32_16x16x32_f16 v[154:157], v[104:107], v[140:143], v[154:157]
	s_waitcnt lgkmcnt(0)
	v_mfma_f32_16x16x32_f16 v[48:51], v[104:107], v[144:147], v[50:53]
	global_load_dwordx4 v[104:107], v[0:1], off offset:384
	v_mfma_f32_16x16x32_f16 v[158:161], v[124:127], v[140:143], v[158:161]
	v_mfma_f32_16x16x32_f16 v[24:27], v[124:127], v[144:147], v[24:27]
	v_mfma_f32_16x16x32_f16 v[190:193], v[162:165], v[140:143], v[190:193]
	v_mfma_f32_16x16x32_f16 v[40:43], v[162:165], v[144:147], v[40:43]
	v_mfma_f32_16x16x32_f16 v[120:123], v[194:197], v[140:143], v[120:123]
	global_load_dwordx4 v[140:143], v[2:3], off offset:384
	global_load_dwordx4 v[198:201], v[4:5], off offset:384
	global_load_dwordx4 v[202:205], v[6:7], off offset:384
	global_load_dwordx4 v[124:127], v[8:9], off offset:384
	global_load_dwordx4 v[220:223], v[10:11], off offset:384
	global_load_dwordx4 v[224:227], v[12:13], off offset:384
	global_load_dwordx4 v[228:231], v[14:15], off offset:384
	s_waitcnt lgkmcnt(0)
	s_barrier
; #define GL_LOAD(s_, kt_) if (VAR != 1) { a##s_##0 = GL_A(0, kt_); a##s_##1 = GL_A(1, kt_); a##s_##2 = GL_A(2, kt_); a##s_##3 = GL_A(3, kt_); b##s_##0 = GL_B(0, kt_); b##s_##1 = GL_B(1, kt_); b##s_##2 = GL_B(2, kt_); b##s_##3 = GL_B(3, kt_); }
; #define LDS_STORE(s_, buf_) if (VAR != 2) { LDS_ST1(sA, 0, buf_, a##s_##0) LDS_ST1(sA, 1, buf_, a##s_##1) LDS_ST1(sA, 2, buf_, a##s_##2) LDS_ST1(sA, 3, buf_, a##s_##3) LDS_ST1(sB, 0, buf_, b##s_##0) LDS_ST1(sB, 1, buf_, b##s_##1) LDS_ST1(sB, 2, buf_, b##s_##2) LDS_ST1(sB, 3, buf_, b##s_##3) }
;     ...
;   GL_LOAD(0, 0)
;   GL_LOAD(1, 1)
;   LDS_STORE(0, 0)
;   if (VAR != 4) __syncthreads();
; #pragma unroll
;   for (int kt = 0; kt < nk; kt += 2) {
;     if (kt + 2 < nk) { GL_LOAD(0, kt + 2) }
;     MMA_TILE(0)
;     LDS_STORE(1, 1)
;     if (VAR != 4) __syncthreads();
;     if (kt + 3 < nk) { GL_LOAD(1, kt + 3) }
;     MMA_TILE(1)
;     if (kt + 2 < nk) { LDS_STORE(0, 0) }
;     if (VAR != 4) __syncthreads();
	v_mfma_f32_16x16x32_f16 v[52:55], v[194:197], v[144:147], v[54:57]
	ds_read_b128 v[162:165], v20 offset:32768
	ds_read_b128 v[144:147], v21
	s_waitcnt lgkmcnt(0)
	v_mfma_f32_16x16x32_f16 v[36:39], v[162:165], v[144:147], v[36:39]
	ds_read_b128 v[56:59], v20 offset:34816
	ds_read_b128 v[166:169], v21 offset:2048
	s_waitcnt lgkmcnt(0)
	v_mfma_f32_16x16x32_f16 v[116:119], v[162:165], v[166:169], v[116:119]
	ds_read_b128 v[194:197], v20 offset:36864
	v_mfma_f32_16x16x32_f16 v[44:47], v[56:59], v[144:147], v[44:47]
	ds_read_b128 v[206:209], v20 offset:38912
	v_mfma_f32_16x16x32_f16 v[128:131], v[56:59], v[166:169], v[128:131]
	s_waitcnt vmcnt(7)
	ds_write_b128 v16, v[104:107] offset:16384
	s_waitcnt lgkmcnt(2)
	v_mfma_f32_16x16x32_f16 v[132:135], v[194:197], v[144:147], v[132:135]
	s_waitcnt vmcnt(6)
	ds_write_b128 v17, v[140:143] offset:16384
	v_mfma_f32_16x16x32_f16 v[136:139], v[194:197], v[166:169], v[136:139]
	s_waitcnt vmcnt(5)
	ds_write_b128 v18, v[198:201] offset:16384
	s_waitcnt lgkmcnt(3)
	v_mfma_f32_16x16x32_f16 v[28:31], v[206:209], v[144:147], v[28:31]
	ds_read_b128 v[144:147], v21 offset:4096
	v_mfma_f32_16x16x32_f16 v[32:35], v[206:209], v[166:169], v[32:35]
	ds_read_b128 v[166:169], v21 offset:6144
	s_waitcnt lgkmcnt(1)
	v_mfma_f32_16x16x32_f16 v[154:157], v[162:165], v[144:147], v[154:157]
	s_waitcnt vmcnt(4)
	ds_write_b128 v19, v[202:205] offset:16384
	s_waitcnt lgkmcnt(1)
	v_mfma_f32_16x16x32_f16 v[48:51], v[162:165], v[166:169], v[48:51]
	ds_read_b128 v[162:165], v22
	v_mfma_f32_16x16x32_f16 v[158:161], v[56:59], v[144:147], v[158:161]
	s_waitcnt vmcnt(3)
	ds_write_b128 v16, v[124:127] offset:49152
	v_mfma_f32_16x16x32_f16 v[24:27], v[56:59], v[166:169], v[24:27]
	ds_read_b128 v[56:59], v23 offset:32768
	v_mfma_f32_16x16x32_f16 v[190:193], v[194:197], v[144:147], v[190:193]
	s_waitcnt vmcnt(2)
	ds_write_b128 v17, v[220:223] offset:49152
	v_mfma_f32_16x16x32_f16 v[40:43], v[194:197], v[166:169], v[40:43]
	ds_read_b128 v[194:197], v23 offset:36864
	v_mfma_f32_16x16x32_f16 v[120:123], v[206:209], v[144:147], v[120:123]
	ds_read_b128 v[144:147], v23 offset:34816
	v_mfma_f32_16x16x32_f16 v[52:55], v[206:209], v[166:169], v[52:55]
	ds_read_b128 v[166:169], v22 offset:2048
	s_waitcnt lgkmcnt(4)
	v_mfma_f32_16x16x32_f16 v[36:39], v[56:59], v[162:165], v[36:39]
	ds_read_b128 v[206:209], v23 offset:38912
	s_waitcnt lgkmcnt(1)
	v_mfma_f32_16x16x32_f16 v[116:119], v[56:59], v[166:169], v[116:119]
	s_waitcnt vmcnt(1)
	ds_write_b128 v18, v[224:227] offset:49152
	v_mfma_f32_16x16x32_f16 v[44:47], v[144:147], v[162:165], v[44:47]
	s_waitcnt vmcnt(0)
	ds_write_b128 v19, v[228:231] offset:49152
	v_mfma_f32_16x16x32_f16 v[128:131], v[144:147], v[166:169], v[128:131]
	v_mfma_f32_16x16x32_f16 v[132:135], v[194:197], v[162:165], v[132:135]
	v_mfma_f32_16x16x32_f16 v[136:139], v[194:197], v[166:169], v[136:139]
	s_waitcnt lgkmcnt(2)
	v_mfma_f32_16x16x32_f16 v[28:31], v[206:209], v[162:165], v[28:31]
	ds_read_b128 v[162:165], v22 offset:4096
	v_mfma_f32_16x16x32_f16 v[32:35], v[206:209], v[166:169], v[32:35]
	ds_read_b128 v[166:169], v22 offset:6144
	s_waitcnt lgkmcnt(1)
	v_mfma_f32_16x16x32_f16 v[154:157], v[56:59], v[162:165], v[154:157]
	s_waitcnt lgkmcnt(0)
	v_mfma_f32_16x16x32_f16 v[48:51], v[56:59], v[166:169], v[48:51]
	global_load_dwordx4 v[56:59], v[0:1], off offset:512
	v_mfma_f32_16x16x32_f16 v[158:161], v[144:147], v[162:165], v[158:161]
	v_mfma_f32_16x16x32_f16 v[24:27], v[144:147], v[166:169], v[24:27]
	v_mfma_f32_16x16x32_f16 v[190:193], v[194:197], v[162:165], v[190:193]
	v_mfma_f32_16x16x32_f16 v[40:43], v[194:197], v[166:169], v[40:43]
	v_mfma_f32_16x16x32_f16 v[120:123], v[206:209], v[162:165], v[120:123]
	global_load_dwordx4 v[162:165], v[2:3], off offset:512
	global_load_dwordx4 v[210:213], v[4:5], off offset:512
	global_load_dwordx4 v[232:235], v[6:7], off offset:512
	global_load_dwordx4 v[144:147], v[8:9], off offset:512
	global_load_dwordx4 v[236:239], v[10:11], off offset:512
	global_load_dwordx4 v[240:243], v[12:13], off offset:512
	global_load_dwordx4 v[244:247], v[14:15], off offset:512
	s_waitcnt lgkmcnt(0)
	s_barrier
	v_mfma_f32_16x16x32_f16 v[52:55], v[206:209], v[166:169], v[52:55]
	ds_read_b128 v[104:107], v20 offset:49152
	ds_read_b128 v[140:143], v21 offset:16384
	s_waitcnt lgkmcnt(0)
	v_mfma_f32_16x16x32_f16 v[36:39], v[104:107], v[140:143], v[36:39]
	ds_read_b128 v[124:127], v20 offset:51200
	ds_read_b128 v[166:169], v21 offset:18432
	s_waitcnt lgkmcnt(0)
	v_mfma_f32_16x16x32_f16 v[116:119], v[104:107], v[166:169], v[116:119]
	ds_read_b128 v[194:197], v20 offset:53248
	v_mfma_f32_16x16x32_f16 v[44:47], v[124:127], v[140:143], v[44:47]
	ds_read_b128 v[198:201], v20 offset:55296
	v_mfma_f32_16x16x32_f16 v[128:131], v[124:127], v[166:169], v[128:131]
	s_waitcnt vmcnt(7)
	ds_write_b128 v16, v[56:59]
	s_waitcnt lgkmcnt(2)
	v_mfma_f32_16x16x32_f16 v[132:135], v[194:197], v[140:143], v[132:135]
	s_waitcnt vmcnt(6)
	ds_write_b128 v17, v[162:165]
	v_mfma_f32_16x16x32_f16 v[136:139], v[194:197], v[166:169], v[136:139]
	s_waitcnt vmcnt(5)
	ds_write_b128 v18, v[210:213]
	s_waitcnt lgkmcnt(3)
	v_mfma_f32_16x16x32_f16 v[28:31], v[198:201], v[140:143], v[28:31]
	ds_read_b128 v[140:143], v21 offset:20480
	v_mfma_f32_16x16x32_f16 v[32:35], v[198:201], v[166:169], v[32:35]
	ds_read_b128 v[166:169], v21 offset:22528
	s_waitcnt lgkmcnt(1)
	v_mfma_f32_16x16x32_f16 v[154:157], v[104:107], v[140:143], v[154:157]
	s_waitcnt vmcnt(4)
	ds_write_b128 v19, v[232:235]
	s_waitcnt lgkmcnt(1)
	v_mfma_f32_16x16x32_f16 v[48:51], v[104:107], v[166:169], v[48:51]
	ds_read_b128 v[104:107], v23 offset:49152
	v_mfma_f32_16x16x32_f16 v[158:161], v[124:127], v[140:143], v[158:161]
	s_waitcnt vmcnt(3)
; #define GL_LOAD(s_, kt_) if (VAR != 1) { a##s_##0 = GL_A(0, kt_); a##s_##1 = GL_A(1, kt_); a##s_##2 = GL_A(2, kt_); a##s_##3 = GL_A(3, kt_); b##s_##0 = GL_B(0, kt_); b##s_##1 = GL_B(1, kt_); b##s_##2 = GL_B(2, kt_); b##s_##3 = GL_B(3, kt_); }
; #define LDS_STORE(s_, buf_) if (VAR != 2) { LDS_ST1(sA, 0, buf_, a##s_##0) LDS_ST1(sA, 1, buf_, a##s_##1) LDS_ST1(sA, 2, buf_, a##s_##2) LDS_ST1(sA, 3, buf_, a##s_##3) LDS_ST1(sB, 0, buf_, b##s_##0) LDS_ST1(sB, 1, buf_, b##s_##1) LDS_ST1(sB, 2, buf_, b##s_##2) LDS_ST1(sB, 3, buf_, b##s_##3) }
;     ...
;   GL_LOAD(0, 0)
;   GL_LOAD(1, 1)
;   LDS_STORE(0, 0)
;   if (VAR != 4) __syncthreads();
; #pragma unroll
;   for (int kt = 0; kt < nk; kt += 2) {
;     if (kt + 2 < nk) { GL_LOAD(0, kt + 2) }
;     MMA_TILE(0)
;     LDS_STORE(1, 1)
;     if (VAR != 4) __syncthreads();
;     if (kt + 3 < nk) { GL_LOAD(1, kt + 3) }
;     MMA_TILE(1)
;     if (kt + 2 < nk) { LDS_STORE(0, 0) }
;     if (VAR != 4) __syncthreads();
	ds_write_b128 v16, v[144:147] offset:32768
	v_mfma_f32_16x16x32_f16 v[24:27], v[124:127], v[166:169], v[24:27]
	ds_read_b128 v[124:127], v23 offset:51200
	v_mfma_f32_16x16x32_f16 v[190:193], v[194:197], v[140:143], v[190:193]
	s_waitcnt vmcnt(2)
	ds_write_b128 v17, v[236:239] offset:32768
	v_mfma_f32_16x16x32_f16 v[40:43], v[194:197], v[166:169], v[40:43]
	ds_read_b128 v[194:197], v23 offset:53248
	v_mfma_f32_16x16x32_f16 v[120:123], v[198:201], v[140:143], v[120:123]
	ds_read_b128 v[140:143], v22 offset:16384
	v_mfma_f32_16x16x32_f16 v[52:55], v[198:201], v[166:169], v[52:55]
	ds_read_b128 v[166:169], v22 offset:18432
	s_waitcnt lgkmcnt(1)
	v_mfma_f32_16x16x32_f16 v[36:39], v[104:107], v[140:143], v[36:39]
	ds_read_b128 v[198:201], v23 offset:55296
	s_waitcnt lgkmcnt(1)
	v_mfma_f32_16x16x32_f16 v[116:119], v[104:107], v[166:169], v[116:119]
	s_waitcnt vmcnt(1)
	ds_write_b128 v18, v[240:243] offset:32768
	v_mfma_f32_16x16x32_f16 v[44:47], v[124:127], v[140:143], v[44:47]
	s_waitcnt vmcnt(0)
	ds_write_b128 v19, v[244:247] offset:32768
	v_mfma_f32_16x16x32_f16 v[128:131], v[124:127], v[166:169], v[128:131]
	v_mfma_f32_16x16x32_f16 v[132:135], v[194:197], v[140:143], v[132:135]
	v_mfma_f32_16x16x32_f16 v[136:139], v[194:197], v[166:169], v[136:139]
	s_waitcnt lgkmcnt(2)
	v_mfma_f32_16x16x32_f16 v[28:31], v[198:201], v[140:143], v[28:31]
	ds_read_b128 v[140:143], v22 offset:20480
	v_mfma_f32_16x16x32_f16 v[32:35], v[198:201], v[166:169], v[32:35]
	ds_read_b128 v[166:169], v22 offset:22528
	s_waitcnt lgkmcnt(1)
	v_mfma_f32_16x16x32_f16 v[154:157], v[104:107], v[140:143], v[154:157]
	s_waitcnt lgkmcnt(0)
	v_mfma_f32_16x16x32_f16 v[48:51], v[104:107], v[166:169], v[48:51]
	global_load_dwordx4 v[104:107], v[0:1], off offset:640
	v_mfma_f32_16x16x32_f16 v[158:161], v[124:127], v[140:143], v[158:161]
	v_mfma_f32_16x16x32_f16 v[24:27], v[124:127], v[166:169], v[24:27]
	v_mfma_f32_16x16x32_f16 v[190:193], v[194:197], v[140:143], v[190:193]
	v_mfma_f32_16x16x32_f16 v[40:43], v[194:197], v[166:169], v[40:43]
	v_mfma_f32_16x16x32_f16 v[120:123], v[198:201], v[140:143], v[120:123]
	global_load_dwordx4 v[140:143], v[2:3], off offset:640
	global_load_dwordx4 v[202:205], v[4:5], off offset:640
	global_load_dwordx4 v[206:209], v[6:7], off offset:640
	global_load_dwordx4 v[124:127], v[8:9], off offset:640
	global_load_dwordx4 v[220:223], v[10:11], off offset:640
	global_load_dwordx4 v[224:227], v[12:13], off offset:640
	global_load_dwordx4 v[228:231], v[14:15], off offset:640
	s_waitcnt lgkmcnt(0)
	s_barrier
	v_mfma_f32_16x16x32_f16 v[52:55], v[198:201], v[166:169], v[52:55]
	ds_read_b128 v[56:59], v20 offset:32768
	ds_read_b128 v[162:165], v21
	s_waitcnt lgkmcnt(0)
	v_mfma_f32_16x16x32_f16 v[36:39], v[56:59], v[162:165], v[36:39]
	ds_read_b128 v[144:147], v20 offset:34816
	ds_read_b128 v[166:169], v21 offset:2048
	s_waitcnt lgkmcnt(0)
	v_mfma_f32_16x16x32_f16 v[116:119], v[56:59], v[166:169], v[116:119]
	ds_read_b128 v[194:197], v20 offset:36864
	v_mfma_f32_16x16x32_f16 v[44:47], v[144:147], v[162:165], v[44:47]
	ds_read_b128 v[198:201], v20 offset:38912
	v_mfma_f32_16x16x32_f16 v[128:131], v[144:147], v[166:169], v[128:131]
	s_waitcnt vmcnt(7)
	ds_write_b128 v16, v[104:107] offset:16384
	s_waitcnt lgkmcnt(2)
	v_mfma_f32_16x16x32_f16 v[132:135], v[194:197], v[162:165], v[132:135]
	s_waitcnt vmcnt(6)
	ds_write_b128 v17, v[140:143] offset:16384
	v_mfma_f32_16x16x32_f16 v[136:139], v[194:197], v[166:169], v[136:139]
	s_waitcnt vmcnt(5)
	ds_write_b128 v18, v[202:205] offset:16384
	s_waitcnt lgkmcnt(3)
	v_mfma_f32_16x16x32_f16 v[28:31], v[198:201], v[162:165], v[28:31]
	ds_read_b128 v[162:165], v21 offset:4096
	v_mfma_f32_16x16x32_f16 v[32:35], v[198:201], v[166:169], v[32:35]
	ds_read_b128 v[166:169], v21 offset:6144
	s_waitcnt lgkmcnt(1)
	v_mfma_f32_16x16x32_f16 v[154:157], v[56:59], v[162:165], v[154:157]
	s_waitcnt vmcnt(4)
	ds_write_b128 v19, v[206:209] offset:16384
	s_waitcnt lgkmcnt(1)
	v_mfma_f32_16x16x32_f16 v[48:51], v[56:59], v[166:169], v[48:51]
	ds_read_b128 v[56:59], v23 offset:32768
	v_mfma_f32_16x16x32_f16 v[158:161], v[144:147], v[162:165], v[158:161]
	s_waitcnt vmcnt(3)
	ds_write_b128 v16, v[124:127] offset:49152
	v_mfma_f32_16x16x32_f16 v[24:27], v[144:147], v[166:169], v[24:27]
	ds_read_b128 v[144:147], v23 offset:34816
	v_mfma_f32_16x16x32_f16 v[190:193], v[194:197], v[162:165], v[190:193]
	s_waitcnt vmcnt(2)
	ds_write_b128 v17, v[220:223] offset:49152
	v_mfma_f32_16x16x32_f16 v[40:43], v[194:197], v[166:169], v[40:43]
	ds_read_b128 v[194:197], v23 offset:36864
	v_mfma_f32_16x16x32_f16 v[120:123], v[198:201], v[162:165], v[120:123]
	ds_read_b128 v[162:165], v22
	v_mfma_f32_16x16x32_f16 v[52:55], v[198:201], v[166:169], v[52:55]
	ds_read_b128 v[166:169], v22 offset:2048
	s_waitcnt lgkmcnt(1)
	v_mfma_f32_16x16x32_f16 v[36:39], v[56:59], v[162:165], v[36:39]
	ds_read_b128 v[198:201], v23 offset:38912
	s_waitcnt lgkmcnt(1)
	v_mfma_f32_16x16x32_f16 v[116:119], v[56:59], v[166:169], v[116:119]
	s_waitcnt vmcnt(1)
	ds_write_b128 v18, v[224:227] offset:49152
	v_mfma_f32_16x16x32_f16 v[44:47], v[144:147], v[162:165], v[44:47]
	s_waitcnt vmcnt(0)
	ds_write_b128 v19, v[228:231] offset:49152
	v_mfma_f32_16x16x32_f16 v[128:131], v[144:147], v[166:169], v[128:131]
	v_mfma_f32_16x16x32_f16 v[132:135], v[194:197], v[162:165], v[132:135]
	v_mfma_f32_16x16x32_f16 v[136:139], v[194:197], v[166:169], v[136:139]
	s_waitcnt lgkmcnt(2)
	v_mfma_f32_16x16x32_f16 v[28:31], v[198:201], v[162:165], v[28:31]
	ds_read_b128 v[162:165], v22 offset:4096
	v_mfma_f32_16x16x32_f16 v[32:35], v[198:201], v[166:169], v[32:35]
	ds_read_b128 v[166:169], v22 offset:6144
	s_waitcnt lgkmcnt(1)
	v_mfma_f32_16x16x32_f16 v[154:157], v[56:59], v[162:165], v[154:157]
	s_waitcnt lgkmcnt(0)
	v_mfma_f32_16x16x32_f16 v[48:51], v[56:59], v[166:169], v[48:51]
	global_load_dwordx4 v[56:59], v[0:1], off offset:768
	v_mfma_f32_16x16x32_f16 v[158:161], v[144:147], v[162:165], v[158:161]
	v_mfma_f32_16x16x32_f16 v[24:27], v[144:147], v[166:169], v[24:27]
	v_mfma_f32_16x16x32_f16 v[190:193], v[194:197], v[162:165], v[190:193]
	v_mfma_f32_16x16x32_f16 v[40:43], v[194:197], v[166:169], v[40:43]
	v_mfma_f32_16x16x32_f16 v[120:123], v[198:201], v[162:165], v[120:123]
	global_load_dwordx4 v[162:165], v[2:3], off offset:768
	global_load_dwordx4 v[210:213], v[4:5], off offset:768
	global_load_dwordx4 v[232:235], v[6:7], off offset:768
	global_load_dwordx4 v[144:147], v[8:9], off offset:768
	global_load_dwordx4 v[236:239], v[10:11], off offset:768
	global_load_dwordx4 v[240:243], v[12:13], off offset:768
	global_load_dwordx4 v[244:247], v[14:15], off offset:768
	s_waitcnt lgkmcnt(0)
	s_barrier
; #define GL_LOAD(s_, kt_) if (VAR != 1) { a##s_##0 = GL_A(0, kt_); a##s_##1 = GL_A(1, kt_); a##s_##2 = GL_A(2, kt_); a##s_##3 = GL_A(3, kt_); b##s_##0 = GL_B(0, kt_); b##s_##1 = GL_B(1, kt_); b##s_##2 = GL_B(2, kt_); b##s_##3 = GL_B(3, kt_); }
; #define LDS_STORE(s_, buf_) if (VAR != 2) { LDS_ST1(sA, 0, buf_, a##s_##0) LDS_ST1(sA, 1, buf_, a##s_##1) LDS_ST1(sA, 2, buf_, a##s_##2) LDS_ST1(sA, 3, buf_, a##s_##3) LDS_ST1(sB, 0, buf_, b##s_##0) LDS_ST1(sB, 1, buf_, b##s_##1) LDS_ST1(sB, 2, buf_, b##s_##2) LDS_ST1(sB, 3, buf_, b##s_##3) }
;     ...
;   GL_LOAD(0, 0)
;   GL_LOAD(1, 1)
;   LDS_STORE(0, 0)
;   if (VAR != 4) __syncthreads();
; #pragma unroll
;   for (int kt = 0; kt < nk; kt += 2) {
;     if (kt + 2 < nk) { GL_LOAD(0, kt + 2) }
;     MMA_TILE(0)
;     LDS_STORE(1, 1)
;     if (VAR != 4) __syncthreads();
;     if (kt + 3 < nk) { GL_LOAD(1, kt + 3) }
;     MMA_TILE(1)
;     if (kt + 2 < nk) { LDS_STORE(0, 0) }
;     if (VAR != 4) __syncthreads();
	v_mfma_f32_16x16x32_f16 v[52:55], v[198:201], v[166:169], v[52:55]
	ds_read_b128 v[104:107], v20 offset:49152
	ds_read_b128 v[140:143], v21 offset:16384
	s_waitcnt lgkmcnt(0)
	v_mfma_f32_16x16x32_f16 v[36:39], v[104:107], v[140:143], v[36:39]
	ds_read_b128 v[124:127], v20 offset:51200
	ds_read_b128 v[166:169], v21 offset:18432
	s_waitcnt lgkmcnt(0)
	v_mfma_f32_16x16x32_f16 v[116:119], v[104:107], v[166:169], v[116:119]
	ds_read_b128 v[194:197], v20 offset:53248
	v_mfma_f32_16x16x32_f16 v[44:47], v[124:127], v[140:143], v[44:47]
	ds_read_b128 v[198:201], v20 offset:55296
	v_mfma_f32_16x16x32_f16 v[128:131], v[124:127], v[166:169], v[128:131]
	s_waitcnt vmcnt(7)
	ds_write_b128 v16, v[56:59]
	s_waitcnt lgkmcnt(2)
	v_mfma_f32_16x16x32_f16 v[132:135], v[194:197], v[140:143], v[132:135]
	s_waitcnt vmcnt(6)
	ds_write_b128 v17, v[162:165]
	v_mfma_f32_16x16x32_f16 v[136:139], v[194:197], v[166:169], v[136:139]
	s_waitcnt vmcnt(5)
	ds_write_b128 v18, v[210:213]
	s_waitcnt lgkmcnt(3)
	v_mfma_f32_16x16x32_f16 v[28:31], v[198:201], v[140:143], v[28:31]
	ds_read_b128 v[140:143], v21 offset:20480
	v_mfma_f32_16x16x32_f16 v[32:35], v[198:201], v[166:169], v[32:35]
	ds_read_b128 v[166:169], v21 offset:22528
	s_waitcnt lgkmcnt(1)
	v_mfma_f32_16x16x32_f16 v[154:157], v[104:107], v[140:143], v[154:157]
	s_waitcnt vmcnt(4)
	ds_write_b128 v19, v[232:235]
	s_waitcnt lgkmcnt(1)
	v_mfma_f32_16x16x32_f16 v[48:51], v[104:107], v[166:169], v[48:51]
	ds_read_b128 v[104:107], v23 offset:49152
	v_mfma_f32_16x16x32_f16 v[158:161], v[124:127], v[140:143], v[158:161]
	s_waitcnt vmcnt(3)
	ds_write_b128 v16, v[144:147] offset:32768
	v_mfma_f32_16x16x32_f16 v[24:27], v[124:127], v[166:169], v[24:27]
	ds_read_b128 v[124:127], v23 offset:51200
	v_mfma_f32_16x16x32_f16 v[190:193], v[194:197], v[140:143], v[190:193]
	s_waitcnt vmcnt(2)
	ds_write_b128 v17, v[236:239] offset:32768
	v_mfma_f32_16x16x32_f16 v[40:43], v[194:197], v[166:169], v[40:43]
	ds_read_b128 v[194:197], v23 offset:53248
	v_mfma_f32_16x16x32_f16 v[120:123], v[198:201], v[140:143], v[120:123]
	ds_read_b128 v[140:143], v22 offset:16384
	v_mfma_f32_16x16x32_f16 v[52:55], v[198:201], v[166:169], v[52:55]
	ds_read_b128 v[166:169], v22 offset:18432
	s_waitcnt lgkmcnt(1)
	v_mfma_f32_16x16x32_f16 v[36:39], v[104:107], v[140:143], v[36:39]
	ds_read_b128 v[198:201], v23 offset:55296
	s_waitcnt lgkmcnt(1)
	v_mfma_f32_16x16x32_f16 v[116:119], v[104:107], v[166:169], v[116:119]
	s_waitcnt vmcnt(1)
	ds_write_b128 v18, v[240:243] offset:32768
	v_mfma_f32_16x16x32_f16 v[44:47], v[124:127], v[140:143], v[44:47]
	s_waitcnt vmcnt(0)
	ds_write_b128 v19, v[244:247] offset:32768
	v_mfma_f32_16x16x32_f16 v[128:131], v[124:127], v[166:169], v[128:131]
	v_mfma_f32_16x16x32_f16 v[132:135], v[194:197], v[140:143], v[132:135]
	v_mfma_f32_16x16x32_f16 v[136:139], v[194:197], v[166:169], v[136:139]
	s_waitcnt lgkmcnt(2)
	v_mfma_f32_16x16x32_f16 v[28:31], v[198:201], v[140:143], v[28:31]
	ds_read_b128 v[140:143], v22 offset:20480
	v_mfma_f32_16x16x32_f16 v[32:35], v[198:201], v[166:169], v[32:35]
	ds_read_b128 v[166:169], v22 offset:22528
	s_waitcnt lgkmcnt(1)
	v_mfma_f32_16x16x32_f16 v[154:157], v[104:107], v[140:143], v[154:157]
	s_waitcnt lgkmcnt(0)
	v_mfma_f32_16x16x32_f16 v[48:51], v[104:107], v[166:169], v[48:51]
	global_load_dwordx4 v[104:107], v[0:1], off offset:896
	global_load_dwordx4 v[0:3], v[2:3], off offset:896
	v_mfma_f32_16x16x32_f16 v[158:161], v[124:127], v[140:143], v[158:161]
	v_mfma_f32_16x16x32_f16 v[24:27], v[124:127], v[166:169], v[24:27]
	v_mfma_f32_16x16x32_f16 v[190:193], v[194:197], v[140:143], v[190:193]
	v_mfma_f32_16x16x32_f16 v[40:43], v[194:197], v[166:169], v[40:43]
	v_mfma_f32_16x16x32_f16 v[120:123], v[198:201], v[140:143], v[120:123]
	global_load_dwordx4 v[140:143], v[4:5], off offset:896
	global_load_dwordx4 v[4:7], v[6:7], off offset:896
	global_load_dwordx4 v[124:127], v[8:9], off offset:896
	global_load_dwordx4 v[8:11], v[10:11], off offset:896
	global_load_dwordx4 v[202:205], v[12:13], off offset:896
	global_load_dwordx4 v[12:15], v[14:15], off offset:896
	s_waitcnt lgkmcnt(0)
	s_barrier
	ds_read_b128 v[56:59], v20 offset:32768
	v_mfma_f32_16x16x32_f16 v[52:55], v[198:201], v[166:169], v[52:55]
	ds_read_b128 v[144:147], v20 offset:34816
	ds_read_b128 v[162:165], v21
	ds_read_b128 v[166:169], v21 offset:2048
	ds_read_b128 v[194:197], v20 offset:36864
	ds_read_b128 v[198:201], v20 offset:38912
	s_waitcnt lgkmcnt(3)
	v_mfma_f32_16x16x32_f16 v[36:39], v[56:59], v[162:165], v[36:39]
	v_mfma_f32_16x16x32_f16 v[44:47], v[144:147], v[162:165], v[44:47]
	s_waitcnt lgkmcnt(1)
	v_mfma_f32_16x16x32_f16 v[132:135], v[194:197], v[162:165], v[132:135]
	s_waitcnt lgkmcnt(0)
	v_mfma_f32_16x16x32_f16 v[28:31], v[198:201], v[162:165], v[28:31]
	v_mfma_f32_16x16x32_f16 v[116:119], v[56:59], v[166:169], v[116:119]
	v_mfma_f32_16x16x32_f16 v[128:131], v[144:147], v[166:169], v[128:131]
	v_mfma_f32_16x16x32_f16 v[136:139], v[194:197], v[166:169], v[136:139]
	v_mfma_f32_16x16x32_f16 v[32:35], v[198:201], v[166:169], v[32:35]
	ds_read_b128 v[162:165], v21 offset:4096
	ds_read_b128 v[166:169], v21 offset:6144
	s_waitcnt lgkmcnt(1)
	v_mfma_f32_16x16x32_f16 v[154:157], v[56:59], v[162:165], v[154:157]
	v_mfma_f32_16x16x32_f16 v[158:161], v[144:147], v[162:165], v[158:161]
	v_mfma_f32_16x16x32_f16 v[190:193], v[194:197], v[162:165], v[190:193]
	v_mfma_f32_16x16x32_f16 v[120:123], v[198:201], v[162:165], v[120:123]
	s_waitcnt lgkmcnt(0)
; DI unsigned pack2(float lo, float hi) { f2_t v = {lo, hi}; h2_t b = __builtin_convertvector(v, h2_t); return __builtin_bit_cast(unsigned, b); }
; DI float lo_f(unsigned u) { return (float)(__builtin_bit_cast(h2_t, u)[0]); }
; DI float hi_f(unsigned u) { return (float)(__builtin_bit_cast(h2_t, u)[1]); }
; #define GL_LOAD(s_, kt_) if (VAR != 1) { a##s_##0 = GL_A(0, kt_); a##s_##1 = GL_A(1, kt_); a##s_##2 = GL_A(2, kt_); a##s_##3 = GL_A(3, kt_); b##s_##0 = GL_B(0, kt_); b##s_##1 = GL_B(1, kt_); b##s_##2 = GL_B(2, kt_); b##s_##3 = GL_B(3, kt_); }
; #define LDS_STORE(s_, buf_) if (VAR != 2) { LDS_ST1(sA, 0, buf_, a##s_##0) LDS_ST1(sA, 1, buf_, a##s_##1) LDS_ST1(sA, 2, buf_, a##s_##2) LDS_ST1(sA, 3, buf_, a##s_##3) LDS_ST1(sB, 0, buf_, b##s_##0) LDS_ST1(sB, 1, buf_, b##s_##1) LDS_ST1(sB, 2, buf_, b##s_##2) LDS_ST1(sB, 3, buf_, b##s_##3) }
;     ...
;   for (int kt = 0; kt < nk; kt += 2) {
;     if (kt + 2 < nk) { GL_LOAD(0, kt + 2) }
;     MMA_TILE(0)
;     LDS_STORE(1, 1)
;     if (VAR != 4) __syncthreads();
;     if (kt + 3 < nk) { GL_LOAD(1, kt + 3) }
;     MMA_TILE(1)
;     if (kt + 2 < nk) { LDS_STORE(0, 0) }
;     if (VAR != 4) __syncthreads();
; DI void phase_merge(const Params& P, int l, char* smem) {
;     ...
;       for (int mt = 0; mt < 4; ++mt) {
;         const int row = row0 + mt * 16 + lr;
; #pragma unroll
;         for (int nt = 0; nt < 4; ++nt) {
;           const uint2 gu = *(const uint2*)(Pb + (size_t)row * PW + C_GL + br * 1024 + col0 + nt * 16 + 4 * g);
;           float t0 = lo_f(gu.x) * acc[mt][nt][0], t1 = hi_f(gu.x) * acc[mt][nt][1], t2 = lo_f(gu.y) * acc[mt][nt][2], t3 = hi_f(gu.y) * acc[mt][nt][3];
;           if (br > 0) { t0 += lo_f(tot[mt][nt][0]); t1 += hi_f(tot[mt][nt][0]); t2 += lo_f(tot[mt][nt][1]); t3 += hi_f(tot[mt][nt][1]); }
;           tot[mt][nt][0] = pack2(t0, t1); tot[mt][nt][1] = pack2(t2, t3);
	v_mfma_f32_16x16x32_f16 v[48:51], v[56:59], v[166:169], v[48:51]
	ds_read_b128 v[56:59], v23 offset:32768
	v_mfma_f32_16x16x32_f16 v[24:27], v[144:147], v[166:169], v[24:27]
	v_mfma_f32_16x16x32_f16 v[40:43], v[194:197], v[166:169], v[40:43]
	v_mfma_f32_16x16x32_f16 v[52:55], v[198:201], v[166:169], v[52:55]
	ds_read_b128 v[144:147], v23 offset:34816
	ds_read_b128 v[162:165], v22
	ds_read_b128 v[166:169], v22 offset:2048
	ds_read_b128 v[194:197], v23 offset:36864
	ds_read_b128 v[198:201], v23 offset:38912
	s_waitcnt lgkmcnt(3)
	v_mfma_f32_16x16x32_f16 v[36:39], v[56:59], v[162:165], v[36:39]
	v_mfma_f32_16x16x32_f16 v[44:47], v[144:147], v[162:165], v[44:47]
	s_waitcnt lgkmcnt(1)
	v_mfma_f32_16x16x32_f16 v[132:135], v[194:197], v[162:165], v[132:135]
	s_waitcnt lgkmcnt(0)
	v_mfma_f32_16x16x32_f16 v[28:31], v[198:201], v[162:165], v[28:31]
	v_mfma_f32_16x16x32_f16 v[116:119], v[56:59], v[166:169], v[116:119]
	v_mfma_f32_16x16x32_f16 v[128:131], v[144:147], v[166:169], v[128:131]
	v_mfma_f32_16x16x32_f16 v[136:139], v[194:197], v[166:169], v[136:139]
	v_mfma_f32_16x16x32_f16 v[32:35], v[198:201], v[166:169], v[32:35]
	ds_read_b128 v[162:165], v22 offset:4096
	ds_read_b128 v[166:169], v22 offset:6144
	s_waitcnt vmcnt(7)
	ds_write_b128 v16, v[104:107] offset:16384
	s_waitcnt vmcnt(6)
	ds_write_b128 v17, v[0:3] offset:16384
	s_waitcnt vmcnt(5)
	ds_write_b128 v18, v[140:143] offset:16384
	s_waitcnt vmcnt(4)
	ds_write_b128 v19, v[4:7] offset:16384
	s_waitcnt vmcnt(3)
	ds_write_b128 v16, v[124:127] offset:49152
	s_waitcnt vmcnt(2)
	ds_write_b128 v17, v[8:11] offset:49152
	s_waitcnt vmcnt(1)
	ds_write_b128 v18, v[202:205] offset:49152
	s_waitcnt vmcnt(0)
	ds_write_b128 v19, v[12:15] offset:49152
	s_waitcnt lgkmcnt(0)
	v_mfma_f32_16x16x32_f16 v[154:157], v[56:59], v[162:165], v[154:157]
	s_barrier
	ds_read_b128 v[0:3], v20 offset:49152
	v_mfma_f32_16x16x32_f16 v[48:51], v[56:59], v[166:169], v[48:51]
	ds_read_b128 v[8:11], v20 offset:51200
	ds_read_b128 v[12:15], v21 offset:16384
	ds_read_b128 v[16:19], v21 offset:18432
	ds_read_b128 v[56:59], v20 offset:55296
	v_mfma_f32_16x16x32_f16 v[4:7], v[198:201], v[166:169], v[52:55]
	s_nop 2
	ds_read_b128 v[52:55], v20 offset:53248
	s_waitcnt lgkmcnt(3)
	v_mfma_f32_16x16x32_f16 v[36:39], v[0:3], v[12:15], v[36:39]
	v_mfma_f32_16x16x32_f16 v[44:47], v[8:11], v[12:15], v[44:47]
	s_waitcnt lgkmcnt(0)
	v_mfma_f32_16x16x32_f16 v[104:107], v[52:55], v[12:15], v[132:135]
	v_mfma_f32_16x16x32_f16 v[12:15], v[56:59], v[12:15], v[28:31]
	v_mfma_f32_16x16x32_f16 v[28:31], v[0:3], v[16:19], v[116:119]
	v_mfma_f32_16x16x32_f16 v[116:119], v[8:11], v[16:19], v[128:131]
	v_mfma_f32_16x16x32_f16 v[124:127], v[52:55], v[16:19], v[136:139]
	v_mfma_f32_16x16x32_f16 v[16:19], v[56:59], v[16:19], v[32:35]
	s_nop 2
	ds_read_b128 v[32:35], v21 offset:20480
	ds_read_b128 v[128:131], v21 offset:22528
	v_mfma_f32_16x16x32_f16 v[158:161], v[144:147], v[162:165], v[158:161]
	v_mfma_f32_16x16x32_f16 v[190:193], v[194:197], v[162:165], v[190:193]
	v_mfma_f32_16x16x32_f16 v[120:123], v[198:201], v[162:165], v[120:123]
	v_mfma_f32_16x16x32_f16 v[24:27], v[144:147], v[166:169], v[24:27]
	v_mfma_f32_16x16x32_f16 v[40:43], v[194:197], v[166:169], v[40:43]
	s_waitcnt lgkmcnt(1)
	v_mfma_f32_16x16x32_f16 v[132:135], v[0:3], v[32:35], v[154:157]
	v_mfma_f32_16x16x32_f16 v[136:139], v[8:11], v[32:35], v[158:161]
	s_nop 1
	ds_read_b128 v[154:157], v23 offset:49152
	v_mfma_f32_16x16x32_f16 v[140:143], v[52:55], v[32:35], v[190:193]
	v_mfma_f32_16x16x32_f16 v[120:123], v[56:59], v[32:35], v[120:123]
	s_waitcnt lgkmcnt(1)
	v_mfma_f32_16x16x32_f16 v[0:3], v[0:3], v[128:131], v[48:51]
	v_mfma_f32_16x16x32_f16 v[8:11], v[8:11], v[128:131], v[24:27]
	v_mfma_f32_16x16x32_f16 v[144:147], v[52:55], v[128:131], v[40:43]
	v_mfma_f32_16x16x32_f16 v[128:131], v[56:59], v[128:131], v[4:7]
	s_nop 2
	ds_read_b128 v[4:7], v23 offset:51200
	ds_read_b128 v[24:27], v22 offset:16384
	ds_read_b128 v[32:35], v22 offset:18432
	ds_read_b128 v[162:165], v23 offset:53248
	ds_read_b128 v[166:169], v23 offset:55296
	s_waitcnt lgkmcnt(0)
	v_mfma_f32_16x16x32_f16 v[48:51], v[166:169], v[24:27], v[12:15]
	v_mfma_f32_16x16x32_f16 v[40:43], v[4:7], v[32:35], v[116:119]
	s_nop 1
	ds_read_b128 v[12:15], v22 offset:20480
	ds_read_b128 v[116:119], v22 offset:22528
	s_waitcnt lgkmcnt(0)
	s_barrier
	s_setprio 0
	v_mfma_f32_16x16x32_f16 v[158:161], v[154:157], v[24:27], v[36:39]
	v_mfma_f32_16x16x32_f16 v[56:59], v[4:7], v[24:27], v[44:47]
	v_mfma_f32_16x16x32_f16 v[52:55], v[162:165], v[24:27], v[104:107]
	v_mfma_f32_16x16x32_f16 v[44:47], v[154:157], v[32:35], v[28:31]
	v_mfma_f32_16x16x32_f16 v[36:39], v[162:165], v[32:35], v[124:127]
	v_mfma_f32_16x16x32_f16 v[32:35], v[166:169], v[32:35], v[16:19]
	v_mfma_f32_16x16x32_f16 v[28:31], v[154:157], v[12:15], v[132:135]
	v_mfma_f32_16x16x32_f16 v[24:27], v[4:7], v[12:15], v[136:139]
	v_mfma_f32_16x16x32_f16 v[20:23], v[162:165], v[12:15], v[140:143]
	v_mfma_f32_16x16x32_f16 v[16:19], v[166:169], v[12:15], v[120:123]
	v_mfma_f32_16x16x32_f16 v[12:15], v[154:157], v[116:119], v[0:3]
	s_nop 2
	global_load_dwordx2 v[154:155], v[108:109], off offset:-64
	global_load_dwordx2 v[156:157], v[108:109], off offset:-32
	global_load_dwordx2 v[120:121], v[108:109], off
	global_load_dwordx2 v[122:123], v[108:109], off offset:32
	v_lshl_add_u64 v[124:125], v[82:83], 0, s[4:5]
	global_load_dwordx2 v[124:125], v[124:125], off offset:-64
	v_lshl_add_u64 v[126:127], v[82:83], 0, s[4:5]
	global_load_dwordx2 v[126:127], v[126:127], off offset:-32
	v_mfma_f32_16x16x32_f16 v[8:11], v[4:7], v[116:119], v[8:11]
	s_waitcnt vmcnt(5)
	v_cvt_f32_f16_e32 v2, v154
	v_cvt_f32_f16_sdwa v3, v154 dst_sel:DWORD dst_unused:UNUSED_PAD src0_sel:WORD_1
	v_cvt_f32_f16_e32 v0, v155
	v_cvt_f32_f16_sdwa v1, v155 dst_sel:DWORD dst_unused:UNUSED_PAD src0_sel:WORD_1
	v_lshl_add_u64 v[154:155], v[82:83], 0, s[4:5]
	global_load_dwordx2 v[154:155], v[154:155], off
	v_mfma_f32_16x16x32_f16 v[4:7], v[162:165], v[116:119], v[144:147]
	v_mul_f32_e64 v104, v158, v2
	v_mul_f32_e64 v105, v159, v3
	v_pk_mul_f32 v[106:107], v[160:161], v[0:1]
	v_mfma_f32_16x16x32_f16 v[0:3], v[166:169], v[116:119], v[128:131]
	s_cbranch_vccnz .LBB0_1163
	v_cvt_f32_f16_sdwa v117, v102 dst_sel:DWORD dst_unused:UNUSED_PAD src0_sel:WORD_1
	v_cvt_f32_f16_e32 v116, v102
	v_pk_add_f32 v[104:105], v[104:105], v[116:117]
	v_cvt_f32_f16_sdwa v117, v103 dst_sel:DWORD dst_unused:UNUSED_PAD src0_sel:WORD_1
	v_cvt_f32_f16_e32 v116, v103
	v_pk_add_f32 v[106:107], v[106:107], v[116:117]
; DI unsigned pack2(float lo, float hi) { f2_t v = {lo, hi}; h2_t b = __builtin_convertvector(v, h2_t); return __builtin_bit_cast(unsigned, b); }
; DI float lo_f(unsigned u) { return (float)(__builtin_bit_cast(h2_t, u)[0]); }
; DI float hi_f(unsigned u) { return (float)(__builtin_bit_cast(h2_t, u)[1]); }
; DI void phase_merge(const Params& P, int l, char* smem) {
;     ...
;       for (int mt = 0; mt < 4; ++mt) {
;         const int row = row0 + mt * 16 + lr;
; #pragma unroll
;         for (int nt = 0; nt < 4; ++nt) {
;           const uint2 gu = *(const uint2*)(Pb + (size_t)row * PW + C_GL + br * 1024 + col0 + nt * 16 + 4 * g);
;           float t0 = lo_f(gu.x) * acc[mt][nt][0], t1 = hi_f(gu.x) * acc[mt][nt][1], t2 = lo_f(gu.y) * acc[mt][nt][2], t3 = hi_f(gu.y) * acc[mt][nt][3];
;           if (br > 0) { t0 += lo_f(tot[mt][nt][0]); t1 += hi_f(tot[mt][nt][0]); t2 += lo_f(tot[mt][nt][1]); t3 += hi_f(tot[mt][nt][1]); }
;           tot[mt][nt][0] = pack2(t0, t1); tot[mt][nt][1] = pack2(t2, t3);
.LBB0_1163:
	s_andn2_b64 vcc, exec, s[6:7]
	s_waitcnt vmcnt(5)
	v_cvt_f32_f16_sdwa v117, v156 dst_sel:DWORD dst_unused:UNUSED_PAD src0_sel:WORD_1
	v_cvt_f32_f16_e32 v116, v156
	v_cndmask_b32_e64 v102, 0, 1, s[6:7]
	v_cmp_ne_u32_e64 s[38:39], 1, v102
	v_pk_mul_f32 v[56:57], v[56:57], v[116:117]
	v_cvt_f32_f16_sdwa v117, v157 dst_sel:DWORD dst_unused:UNUSED_PAD src0_sel:WORD_1
	v_cvt_f32_f16_e32 v116, v157
	v_lshl_add_u64 v[156:157], v[82:83], 0, s[4:5]
	global_load_dwordx2 v[156:157], v[156:157], off offset:32
	v_pk_mul_f32 v[58:59], v[58:59], v[116:117]
	s_cbranch_vccnz .LBB0_1165
	v_cvt_f32_f16_sdwa v103, v100 dst_sel:DWORD dst_unused:UNUSED_PAD src0_sel:WORD_1
	v_cvt_f32_f16_e32 v102, v100
	v_pk_add_f32 v[56:57], v[56:57], v[102:103]
	v_cvt_f32_f16_sdwa v103, v101 dst_sel:DWORD dst_unused:UNUSED_PAD src0_sel:WORD_1
	v_cvt_f32_f16_e32 v102, v101
	v_pk_add_f32 v[58:59], v[58:59], v[102:103]
.LBB0_1165:
	s_and_b64 vcc, exec, s[38:39]
	s_waitcnt vmcnt(5)
	v_cvt_f32_f16_sdwa v103, v120 dst_sel:DWORD dst_unused:UNUSED_PAD src0_sel:WORD_1
	v_cvt_f32_f16_e32 v102, v120
	v_pk_mul_f32 v[52:53], v[52:53], v[102:103]
	v_cvt_f32_f16_sdwa v103, v121 dst_sel:DWORD dst_unused:UNUSED_PAD src0_sel:WORD_1
	v_cvt_f32_f16_e32 v102, v121
	v_lshl_add_u64 v[120:121], v[78:79], 0, s[4:5]
	global_load_dwordx2 v[120:121], v[120:121], off offset:-64
	v_pk_mul_f32 v[54:55], v[54:55], v[102:103]
	s_cbranch_vccnz .LBB0_1167
	v_cvt_f32_f16_sdwa v101, v98 dst_sel:DWORD dst_unused:UNUSED_PAD src0_sel:WORD_1
	v_cvt_f32_f16_e32 v100, v98
	v_pk_add_f32 v[52:53], v[52:53], v[100:101]
	v_cvt_f32_f16_sdwa v101, v99 dst_sel:DWORD dst_unused:UNUSED_PAD src0_sel:WORD_1
	v_cvt_f32_f16_e32 v100, v99
	v_pk_add_f32 v[54:55], v[54:55], v[100:101]
.LBB0_1167:
	s_and_b64 vcc, exec, s[38:39]
	s_waitcnt vmcnt(5)
	v_cvt_f32_f16_sdwa v101, v122 dst_sel:DWORD dst_unused:UNUSED_PAD src0_sel:WORD_1
	v_cvt_f32_f16_e32 v100, v122
	v_pk_mul_f32 v[48:49], v[48:49], v[100:101]
	v_cvt_f32_f16_sdwa v101, v123 dst_sel:DWORD dst_unused:UNUSED_PAD src0_sel:WORD_1
	v_cvt_f32_f16_e32 v100, v123
	v_lshl_add_u64 v[122:123], v[78:79], 0, s[4:5]
	global_load_dwordx2 v[122:123], v[122:123], off offset:-32
	v_pk_mul_f32 v[50:51], v[50:51], v[100:101]
	s_cbranch_vccnz .LBB0_1169
	v_cvt_f32_f16_sdwa v99, v96 dst_sel:DWORD dst_unused:UNUSED_PAD src0_sel:WORD_1
	v_cvt_f32_f16_e32 v98, v96
	v_pk_add_f32 v[48:49], v[48:49], v[98:99]
	v_cvt_f32_f16_sdwa v99, v97 dst_sel:DWORD dst_unused:UNUSED_PAD src0_sel:WORD_1
	v_cvt_f32_f16_e32 v98, v97
	v_pk_add_f32 v[50:51], v[50:51], v[98:99]
.LBB0_1169:
	s_and_b64 vcc, exec, s[38:39]
	s_waitcnt vmcnt(5)
	v_cvt_f32_f16_e32 v100, v124
	v_cvt_f32_f16_sdwa v101, v124 dst_sel:DWORD dst_unused:UNUSED_PAD src0_sel:WORD_1
	v_cvt_f32_f16_e32 v98, v125
	v_cvt_f32_f16_sdwa v99, v125 dst_sel:DWORD dst_unused:UNUSED_PAD src0_sel:WORD_1
	v_lshl_add_u64 v[124:125], v[78:79], 0, s[4:5]
	global_load_dwordx2 v[124:125], v[124:125], off
	v_pk_mul_f32 v[44:45], v[44:45], v[100:101]
	v_pk_mul_f32 v[46:47], v[46:47], v[98:99]
	s_cbranch_vccnz .LBB0_1171
	v_cvt_f32_f16_sdwa v99, v94 dst_sel:DWORD dst_unused:UNUSED_PAD src0_sel:WORD_1
	v_cvt_f32_f16_e32 v98, v94
	v_pk_add_f32 v[44:45], v[44:45], v[98:99]
	v_cvt_f32_f16_sdwa v99, v95 dst_sel:DWORD dst_unused:UNUSED_PAD src0_sel:WORD_1
	v_cvt_f32_f16_e32 v98, v95
	v_pk_add_f32 v[46:47], v[46:47], v[98:99]
.LBB0_1171:
	s_and_b64 vcc, exec, s[38:39]
	s_waitcnt vmcnt(5)
	v_cvt_f32_f16_sdwa v99, v126 dst_sel:DWORD dst_unused:UNUSED_PAD src0_sel:WORD_1
	v_cvt_f32_f16_e32 v98, v126
	v_pk_mul_f32 v[40:41], v[40:41], v[98:99]
	v_cvt_f32_f16_sdwa v99, v127 dst_sel:DWORD dst_unused:UNUSED_PAD src0_sel:WORD_1
	v_cvt_f32_f16_e32 v98, v127
	v_lshl_add_u64 v[126:127], v[78:79], 0, s[4:5]
	global_load_dwordx2 v[126:127], v[126:127], off offset:32
	v_pk_mul_f32 v[42:43], v[42:43], v[98:99]
	s_cbranch_vccnz .LBB0_1173
	v_cvt_f32_f16_sdwa v95, v92 dst_sel:DWORD dst_unused:UNUSED_PAD src0_sel:WORD_1
	v_cvt_f32_f16_e32 v94, v92
	v_pk_add_f32 v[40:41], v[40:41], v[94:95]
	v_cvt_f32_f16_sdwa v95, v93 dst_sel:DWORD dst_unused:UNUSED_PAD src0_sel:WORD_1
	v_cvt_f32_f16_e32 v94, v93
	v_pk_add_f32 v[42:43], v[42:43], v[94:95]
.LBB0_1173:
	s_and_b64 vcc, exec, s[38:39]
	s_waitcnt vmcnt(5)
	v_cvt_f32_f16_sdwa v95, v154 dst_sel:DWORD dst_unused:UNUSED_PAD src0_sel:WORD_1
	v_cvt_f32_f16_e32 v94, v154
	v_pk_mul_f32 v[36:37], v[36:37], v[94:95]
	v_cvt_f32_f16_sdwa v95, v155 dst_sel:DWORD dst_unused:UNUSED_PAD src0_sel:WORD_1
	v_cvt_f32_f16_e32 v94, v155
	v_lshl_add_u64 v[154:155], v[76:77], 0, s[4:5]
	global_load_dwordx2 v[154:155], v[154:155], off offset:-64
	v_pk_mul_f32 v[38:39], v[38:39], v[94:95]
	s_cbranch_vccnz .LBB0_1175
	v_cvt_f32_f16_sdwa v93, v90 dst_sel:DWORD dst_unused:UNUSED_PAD src0_sel:WORD_1
	v_cvt_f32_f16_e32 v92, v90
	v_pk_add_f32 v[36:37], v[36:37], v[92:93]
	v_cvt_f32_f16_sdwa v93, v91 dst_sel:DWORD dst_unused:UNUSED_PAD src0_sel:WORD_1
	v_cvt_f32_f16_e32 v92, v91
	v_pk_add_f32 v[38:39], v[38:39], v[92:93]
.LBB0_1175:
	s_and_b64 vcc, exec, s[38:39]
	s_waitcnt vmcnt(5)
	v_cvt_f32_f16_sdwa v93, v156 dst_sel:DWORD dst_unused:UNUSED_PAD src0_sel:WORD_1
	v_cvt_f32_f16_e32 v92, v156
	v_pk_mul_f32 v[32:33], v[32:33], v[92:93]
	v_cvt_f32_f16_sdwa v93, v157 dst_sel:DWORD dst_unused:UNUSED_PAD src0_sel:WORD_1
	v_cvt_f32_f16_e32 v92, v157
	v_lshl_add_u64 v[156:157], v[76:77], 0, s[4:5]
	global_load_dwordx2 v[156:157], v[156:157], off offset:-32
	v_pk_mul_f32 v[34:35], v[34:35], v[92:93]
	s_cbranch_vccnz .LBB0_1177
	v_cvt_f32_f16_sdwa v91, v88 dst_sel:DWORD dst_unused:UNUSED_PAD src0_sel:WORD_1
	v_cvt_f32_f16_e32 v90, v88
	v_pk_add_f32 v[32:33], v[32:33], v[90:91]
	v_cvt_f32_f16_sdwa v91, v89 dst_sel:DWORD dst_unused:UNUSED_PAD src0_sel:WORD_1
	v_cvt_f32_f16_e32 v90, v89
	v_pk_add_f32 v[34:35], v[34:35], v[90:91]
; DI unsigned pack2(float lo, float hi) { f2_t v = {lo, hi}; h2_t b = __builtin_convertvector(v, h2_t); return __builtin_bit_cast(unsigned, b); }
; DI float lo_f(unsigned u) { return (float)(__builtin_bit_cast(h2_t, u)[0]); }
; DI float hi_f(unsigned u) { return (float)(__builtin_bit_cast(h2_t, u)[1]); }
; DI void phase_merge(const Params& P, int l, char* smem) {
;     ...
;       for (int mt = 0; mt < 4; ++mt) {
;         const int row = row0 + mt * 16 + lr;
; #pragma unroll
;         for (int nt = 0; nt < 4; ++nt) {
;           const uint2 gu = *(const uint2*)(Pb + (size_t)row * PW + C_GL + br * 1024 + col0 + nt * 16 + 4 * g);
;           float t0 = lo_f(gu.x) * acc[mt][nt][0], t1 = hi_f(gu.x) * acc[mt][nt][1], t2 = lo_f(gu.y) * acc[mt][nt][2], t3 = hi_f(gu.y) * acc[mt][nt][3];
;           if (br > 0) { t0 += lo_f(tot[mt][nt][0]); t1 += hi_f(tot[mt][nt][0]); t2 += lo_f(tot[mt][nt][1]); t3 += hi_f(tot[mt][nt][1]); }
;           tot[mt][nt][0] = pack2(t0, t1); tot[mt][nt][1] = pack2(t2, t3);
.LBB0_1177:
	s_and_b64 vcc, exec, s[38:39]
	s_waitcnt vmcnt(5)
	v_cvt_f32_f16_e32 v92, v120
	v_cvt_f32_f16_sdwa v93, v120 dst_sel:DWORD dst_unused:UNUSED_PAD src0_sel:WORD_1
	v_cvt_f32_f16_e32 v90, v121
	v_cvt_f32_f16_sdwa v91, v121 dst_sel:DWORD dst_unused:UNUSED_PAD src0_sel:WORD_1
	v_lshl_add_u64 v[120:121], v[76:77], 0, s[4:5]
	global_load_dwordx2 v[120:121], v[120:121], off
	v_pk_mul_f32 v[28:29], v[28:29], v[92:93]
	v_pk_mul_f32 v[30:31], v[30:31], v[90:91]
	s_cbranch_vccnz .LBB0_1179
	v_cvt_f32_f16_sdwa v91, v86 dst_sel:DWORD dst_unused:UNUSED_PAD src0_sel:WORD_1
	v_cvt_f32_f16_e32 v90, v86
	v_pk_add_f32 v[28:29], v[28:29], v[90:91]
	v_cvt_f32_f16_sdwa v91, v87 dst_sel:DWORD dst_unused:UNUSED_PAD src0_sel:WORD_1
	v_cvt_f32_f16_e32 v90, v87
	v_pk_add_f32 v[30:31], v[30:31], v[90:91]
.LBB0_1179:
	s_and_b64 vcc, exec, s[38:39]
	s_waitcnt vmcnt(5)
	v_cvt_f32_f16_sdwa v91, v122 dst_sel:DWORD dst_unused:UNUSED_PAD src0_sel:WORD_1
	v_cvt_f32_f16_e32 v90, v122
	v_pk_mul_f32 v[24:25], v[24:25], v[90:91]
	v_cvt_f32_f16_sdwa v91, v123 dst_sel:DWORD dst_unused:UNUSED_PAD src0_sel:WORD_1
	v_cvt_f32_f16_e32 v90, v123
	v_lshl_add_u64 v[122:123], v[76:77], 0, s[4:5]
	global_load_dwordx2 v[122:123], v[122:123], off offset:32
	v_pk_mul_f32 v[26:27], v[26:27], v[90:91]
	s_cbranch_vccnz .LBB0_1181
	v_cvt_f32_f16_sdwa v87, v84 dst_sel:DWORD dst_unused:UNUSED_PAD src0_sel:WORD_1
	v_cvt_f32_f16_e32 v86, v84
	v_pk_add_f32 v[24:25], v[24:25], v[86:87]
	v_cvt_f32_f16_sdwa v87, v85 dst_sel:DWORD dst_unused:UNUSED_PAD src0_sel:WORD_1
	v_cvt_f32_f16_e32 v86, v85
	v_pk_add_f32 v[26:27], v[26:27], v[86:87]
.LBB0_1181:
	s_and_b64 vcc, exec, s[38:39]
	s_waitcnt vmcnt(5)
	v_cvt_f32_f16_sdwa v87, v124 dst_sel:DWORD dst_unused:UNUSED_PAD src0_sel:WORD_1
	v_cvt_f32_f16_e32 v86, v124
	v_pk_mul_f32 v[20:21], v[20:21], v[86:87]
	v_cvt_f32_f16_sdwa v87, v125 dst_sel:DWORD dst_unused:UNUSED_PAD src0_sel:WORD_1
	v_cvt_f32_f16_e32 v86, v125
	v_pk_mul_f32 v[22:23], v[22:23], v[86:87]
	s_cbranch_vccnz .LBB0_1183
	v_cvt_f32_f16_sdwa v85, v74 dst_sel:DWORD dst_unused:UNUSED_PAD src0_sel:WORD_1
	v_cvt_f32_f16_e32 v84, v74
	v_pk_add_f32 v[20:21], v[20:21], v[84:85]
	v_cvt_f32_f16_sdwa v85, v75 dst_sel:DWORD dst_unused:UNUSED_PAD src0_sel:WORD_1
	v_cvt_f32_f16_e32 v84, v75
	v_pk_add_f32 v[22:23], v[22:23], v[84:85]
.LBB0_1183:
	s_and_b64 vcc, exec, s[38:39]
	s_waitcnt vmcnt(4)
	v_cvt_f32_f16_sdwa v85, v126 dst_sel:DWORD dst_unused:UNUSED_PAD src0_sel:WORD_1
	v_cvt_f32_f16_e32 v84, v126
	v_pk_mul_f32 v[16:17], v[16:17], v[84:85]
	v_cvt_f32_f16_sdwa v85, v127 dst_sel:DWORD dst_unused:UNUSED_PAD src0_sel:WORD_1
	v_cvt_f32_f16_e32 v84, v127
	v_pk_mul_f32 v[18:19], v[18:19], v[84:85]
	s_cbranch_vccnz .LBB0_1185
	v_cvt_f32_f16_sdwa v75, v72 dst_sel:DWORD dst_unused:UNUSED_PAD src0_sel:WORD_1
	v_cvt_f32_f16_e32 v74, v72
	v_pk_add_f32 v[16:17], v[16:17], v[74:75]
	v_cvt_f32_f16_sdwa v75, v73 dst_sel:DWORD dst_unused:UNUSED_PAD src0_sel:WORD_1
	v_cvt_f32_f16_e32 v74, v73
	v_pk_add_f32 v[18:19], v[18:19], v[74:75]
.LBB0_1185:
	s_and_b64 vcc, exec, s[38:39]
	s_waitcnt vmcnt(3)
	v_cvt_f32_f16_e32 v84, v154
	v_cvt_f32_f16_sdwa v85, v154 dst_sel:DWORD dst_unused:UNUSED_PAD src0_sel:WORD_1
	v_cvt_f32_f16_e32 v74, v155
	v_cvt_f32_f16_sdwa v75, v155 dst_sel:DWORD dst_unused:UNUSED_PAD src0_sel:WORD_1
	v_pk_mul_f32 v[12:13], v[12:13], v[84:85]
	v_pk_mul_f32 v[14:15], v[14:15], v[74:75]
	s_cbranch_vccnz .LBB0_1187
	v_cvt_f32_f16_sdwa v75, v70 dst_sel:DWORD dst_unused:UNUSED_PAD src0_sel:WORD_1
	v_cvt_f32_f16_e32 v74, v70
	v_pk_add_f32 v[12:13], v[12:13], v[74:75]
	v_cvt_f32_f16_sdwa v75, v71 dst_sel:DWORD dst_unused:UNUSED_PAD src0_sel:WORD_1
	v_cvt_f32_f16_e32 v74, v71
	v_pk_add_f32 v[14:15], v[14:15], v[74:75]
.LBB0_1187:
	s_and_b64 vcc, exec, s[38:39]
	s_waitcnt vmcnt(2)
	v_cvt_f32_f16_sdwa v75, v156 dst_sel:DWORD dst_unused:UNUSED_PAD src0_sel:WORD_1
	v_cvt_f32_f16_e32 v74, v156
	v_pk_mul_f32 v[8:9], v[8:9], v[74:75]
	v_cvt_f32_f16_sdwa v75, v157 dst_sel:DWORD dst_unused:UNUSED_PAD src0_sel:WORD_1
	v_cvt_f32_f16_e32 v74, v157
	v_pk_mul_f32 v[10:11], v[10:11], v[74:75]
	s_cbranch_vccnz .LBB0_1189
	v_cvt_f32_f16_sdwa v71, v68 dst_sel:DWORD dst_unused:UNUSED_PAD src0_sel:WORD_1
	v_cvt_f32_f16_e32 v70, v68
	v_pk_add_f32 v[8:9], v[8:9], v[70:71]
	v_cvt_f32_f16_sdwa v71, v69 dst_sel:DWORD dst_unused:UNUSED_PAD src0_sel:WORD_1
	v_cvt_f32_f16_e32 v70, v69
	v_pk_add_f32 v[10:11], v[10:11], v[70:71]
.LBB0_1189:
	s_and_b64 vcc, exec, s[38:39]
	s_waitcnt vmcnt(1)
	v_cvt_f32_f16_sdwa v71, v120 dst_sel:DWORD dst_unused:UNUSED_PAD src0_sel:WORD_1
	v_cvt_f32_f16_e32 v70, v120
	v_pk_mul_f32 v[4:5], v[4:5], v[70:71]
	v_cvt_f32_f16_sdwa v71, v121 dst_sel:DWORD dst_unused:UNUSED_PAD src0_sel:WORD_1
	v_cvt_f32_f16_e32 v70, v121
	v_pk_mul_f32 v[6:7], v[6:7], v[70:71]
	s_cbranch_vccnz .LBB0_1191
	v_cvt_f32_f16_sdwa v69, v66 dst_sel:DWORD dst_unused:UNUSED_PAD src0_sel:WORD_1
	v_cvt_f32_f16_e32 v68, v66
	v_pk_add_f32 v[4:5], v[4:5], v[68:69]
	v_cvt_f32_f16_sdwa v69, v67 dst_sel:DWORD dst_unused:UNUSED_PAD src0_sel:WORD_1
	v_cvt_f32_f16_e32 v68, v67
	v_pk_add_f32 v[6:7], v[6:7], v[68:69]
.LBB0_1191:
	s_and_b64 vcc, exec, s[38:39]
	s_waitcnt vmcnt(0)
	v_cvt_f32_f16_sdwa v69, v122 dst_sel:DWORD dst_unused:UNUSED_PAD src0_sel:WORD_1
	v_cvt_f32_f16_e32 v68, v122
	v_pk_mul_f32 v[0:1], v[0:1], v[68:69]
	v_cvt_f32_f16_sdwa v69, v123 dst_sel:DWORD dst_unused:UNUSED_PAD src0_sel:WORD_1
	v_cvt_f32_f16_e32 v68, v123
	v_pk_mul_f32 v[2:3], v[2:3], v[68:69]
	s_cbranch_vccnz .LBB0_1160
	v_cvt_f32_f16_sdwa v67, v64 dst_sel:DWORD dst_unused:UNUSED_PAD src0_sel:WORD_1
	v_cvt_f32_f16_e32 v66, v64
	v_pk_add_f32 v[0:1], v[0:1], v[66:67]
	v_cvt_f32_f16_sdwa v67, v65 dst_sel:DWORD dst_unused:UNUSED_PAD src0_sel:WORD_1
	v_cvt_f32_f16_e32 v66, v65
	v_pk_add_f32 v[2:3], v[2:3], v[66:67]
	s_branch .LBB0_1160
